# P8 SwiGLU epilogue: scale, add-one and final multiplies as packed f32 pairs (40 VALU per row instead of 64), same f32 math and operation order
# baseline (speedup 1.0000x reference)
.Lp8_nonext:
	v_lshl_add_u32 v214, s8, 8, v146
	v_lshl_or_b32 v215, s0, 7, v148
	v_mul_u32_u24_e32 v154, 0x1600, v214
	v_lshl_add_u32 v154, v215, 1, v154
	v_add_u32_e32 v155, 0x16000, v154
	v_add_u32_e32 v156, 0x2c000, v154
	v_add_u32_e32 v157, 0x42000, v154
	v_add_u32_e32 v158, 0xb0000, v154
	v_add_u32_e32 v159, 0xc6000, v154
	v_add_u32_e32 v160, 0xdc000, v154
	v_add_u32_e32 v161, 0xf2000, v154
	s_waitcnt lgkmcnt(0)
	v_add_f32_e32 v174, v174, v175
	v_add_f32_e32 v178, v178, v179
	v_add_f32_e32 v182, v182, v183
	v_add_f32_e32 v186, v186, v187
	v_add_f32_e32 v190, v190, v191
	v_add_f32_e32 v194, v194, v195
	v_add_f32_e32 v198, v198, v199
	v_add_f32_e32 v202, v202, v203
	v_add_f32_e32 v174, v174, v176
	v_add_f32_e32 v178, v178, v180
	v_add_f32_e32 v182, v182, v184
	v_add_f32_e32 v186, v186, v188
	v_add_f32_e32 v190, v190, v192
	v_add_f32_e32 v194, v194, v196
	v_add_f32_e32 v198, v198, v200
	v_add_f32_e32 v202, v202, v204
	v_add_f32_e32 v174, v174, v177
	v_add_f32_e32 v178, v178, v181
	v_add_f32_e32 v182, v182, v185
	v_add_f32_e32 v186, v186, v189
	v_add_f32_e32 v190, v190, v193
	v_add_f32_e32 v194, v194, v197
	v_add_f32_e32 v198, v198, v201
	v_add_f32_e32 v202, v202, v205
	v_fmamk_f32 v174, v174, 0x3a800000, v152
	v_fmamk_f32 v178, v178, 0x3a800000, v152
	v_fmamk_f32 v182, v182, 0x3a800000, v152
	v_fmamk_f32 v186, v186, 0x3a800000, v152
	v_fmamk_f32 v190, v190, 0x3a800000, v152
	v_fmamk_f32 v194, v194, 0x3a800000, v152
	v_fmamk_f32 v198, v198, 0x3a800000, v152
	v_fmamk_f32 v202, v202, 0x3a800000, v152
	v_mul_f32_e32 v175, 0x4b800000, v174
	v_mul_f32_e32 v179, 0x4b800000, v178
	v_mul_f32_e32 v183, 0x4b800000, v182
	v_mul_f32_e32 v187, 0x4b800000, v186
	v_mul_f32_e32 v191, 0x4b800000, v190
	v_mul_f32_e32 v195, 0x4b800000, v194
	v_mul_f32_e32 v199, 0x4b800000, v198
	v_mul_f32_e32 v203, 0x4b800000, v202
	v_cmp_gt_f32_e64 s[74:75], s58, v174
	v_cmp_gt_f32_e64 s[76:77], s58, v178
	v_cmp_gt_f32_e64 s[78:79], s58, v182
	v_cmp_gt_f32_e64 s[80:81], s58, v186
	v_cmp_gt_f32_e64 s[82:83], s58, v190
	v_cmp_gt_f32_e64 s[84:85], s58, v194
	v_cmp_gt_f32_e64 s[86:87], s58, v198
	v_cmp_gt_f32_e64 s[88:89], s58, v202
	v_cndmask_b32_e64 v174, v174, v175, s[74:75]
	v_cndmask_b32_e64 v178, v178, v179, s[76:77]
	v_cndmask_b32_e64 v182, v182, v183, s[78:79]
	v_cndmask_b32_e64 v186, v186, v187, s[80:81]
	v_cndmask_b32_e64 v190, v190, v191, s[82:83]
	v_cndmask_b32_e64 v194, v194, v195, s[84:85]
	v_cndmask_b32_e64 v198, v198, v199, s[86:87]
	v_cndmask_b32_e64 v202, v202, v203, s[88:89]
	v_rsq_f32_e32 v174, v174
	v_rsq_f32_e32 v178, v178
	v_rsq_f32_e32 v182, v182
	v_rsq_f32_e32 v186, v186
	v_rsq_f32_e32 v190, v190
	v_rsq_f32_e32 v194, v194
	v_rsq_f32_e32 v198, v198
	v_rsq_f32_e32 v202, v202
	v_mul_f32_e32 v175, 0x45800000, v174
	v_mul_f32_e32 v179, 0x45800000, v178
	v_mul_f32_e32 v183, 0x45800000, v182
	v_mul_f32_e32 v187, 0x45800000, v186
	v_mul_f32_e32 v191, 0x45800000, v190
	v_mul_f32_e32 v195, 0x45800000, v194
	v_mul_f32_e32 v199, 0x45800000, v198
	v_mul_f32_e32 v203, 0x45800000, v202
	v_cndmask_b32_e64 v206, v174, v175, s[74:75]
	v_cndmask_b32_e64 v207, v178, v179, s[76:77]
	v_cndmask_b32_e64 v208, v182, v183, s[78:79]
	v_cndmask_b32_e64 v209, v186, v187, s[80:81]
	v_cndmask_b32_e64 v210, v190, v191, s[82:83]
	v_cndmask_b32_e64 v211, v194, v195, s[84:85]
	v_cndmask_b32_e64 v212, v198, v199, s[86:87]
	v_cndmask_b32_e64 v213, v202, v203, s[88:89]
	s_mov_b32 s90, 0xbfb8aa3b
	v_pk_mul_f32 v[120:121], v[120:121], v[206:207] op_sel_hi:[1,0]
	v_pk_mul_f32 v[122:123], v[122:123], v[206:207] op_sel_hi:[1,0]
	v_pk_mul_f32 v[116:117], v[116:117], v[206:207] op_sel_hi:[1,0]
	v_pk_mul_f32 v[118:119], v[118:119], v[206:207] op_sel_hi:[1,0]
	v_pk_mul_f32 v[124:125], v[124:125], v[206:207] op_sel_hi:[1,0]
	v_pk_mul_f32 v[126:127], v[126:127], v[206:207] op_sel_hi:[1,0]
	v_pk_mul_f32 v[112:113], v[112:113], v[206:207] op_sel_hi:[1,0]
	v_pk_mul_f32 v[114:115], v[114:115], v[206:207] op_sel_hi:[1,0]
	v_pk_mul_f32 v[174:175], v[120:121], s[90:91] op_sel_hi:[1,0]
	v_pk_mul_f32 v[176:177], v[122:123], s[90:91] op_sel_hi:[1,0]
	v_pk_mul_f32 v[178:179], v[116:117], s[90:91] op_sel_hi:[1,0]
	v_pk_mul_f32 v[180:181], v[118:119], s[90:91] op_sel_hi:[1,0]
	v_exp_f32_e32 v174, v174
	v_exp_f32_e32 v175, v175
	v_exp_f32_e32 v176, v176
	v_exp_f32_e32 v177, v177
	v_exp_f32_e32 v178, v178
	v_exp_f32_e32 v179, v179
	v_exp_f32_e32 v180, v180
	v_exp_f32_e32 v181, v181
	v_pk_add_f32 v[174:175], v[174:175], 1.0 op_sel_hi:[1,0]
	v_pk_add_f32 v[176:177], v[176:177], 1.0 op_sel_hi:[1,0]
	v_pk_add_f32 v[178:179], v[178:179], 1.0 op_sel_hi:[1,0]
	v_pk_add_f32 v[180:181], v[180:181], 1.0 op_sel_hi:[1,0]
	v_rcp_f32_e32 v174, v174
	v_rcp_f32_e32 v175, v175
	v_rcp_f32_e32 v176, v176
	v_rcp_f32_e32 v177, v177
	v_rcp_f32_e32 v178, v178
	v_rcp_f32_e32 v179, v179
	v_rcp_f32_e32 v180, v180
	v_rcp_f32_e32 v181, v181
	v_pk_mul_f32 v[120:121], v[120:121], v[174:175]
	v_pk_mul_f32 v[122:123], v[122:123], v[176:177]
	v_pk_mul_f32 v[116:117], v[116:117], v[178:179]
	v_pk_mul_f32 v[118:119], v[118:119], v[180:181]
	v_pk_mul_f32 v[120:121], v[124:125], v[120:121]
	v_pk_mul_f32 v[122:123], v[126:127], v[122:123]
	v_pk_mul_f32 v[116:117], v[112:113], v[116:117]
	v_pk_mul_f32 v[118:119], v[114:115], v[118:119]
	v_cvt_pk_bf16_f32 v120, v120, v121
	v_cvt_pk_bf16_f32 v121, v122, v123
	v_cvt_pk_bf16_f32 v116, v116, v117
	v_cvt_pk_bf16_f32 v117, v118, v119
	global_store_dwordx2 v154, v[120:121], s[34:35]
	global_store_dwordx2 v154, v[116:117], s[34:35] offset:128
	v_pk_mul_f32 v[108:109], v[108:109], v[206:207] op_sel:[0,1] op_sel_hi:[1,1]
	v_pk_mul_f32 v[110:111], v[110:111], v[206:207] op_sel:[0,1] op_sel_hi:[1,1]
	v_pk_mul_f32 v[100:101], v[100:101], v[206:207] op_sel:[0,1] op_sel_hi:[1,1]
	v_pk_mul_f32 v[102:103], v[102:103], v[206:207] op_sel:[0,1] op_sel_hi:[1,1]
	v_pk_mul_f32 v[104:105], v[104:105], v[206:207] op_sel:[0,1] op_sel_hi:[1,1]
	v_pk_mul_f32 v[106:107], v[106:107], v[206:207] op_sel:[0,1] op_sel_hi:[1,1]
	v_pk_mul_f32 v[96:97], v[96:97], v[206:207] op_sel:[0,1] op_sel_hi:[1,1]
	v_pk_mul_f32 v[98:99], v[98:99], v[206:207] op_sel:[0,1] op_sel_hi:[1,1]
	v_pk_mul_f32 v[174:175], v[108:109], s[90:91] op_sel_hi:[1,0]
	v_pk_mul_f32 v[176:177], v[110:111], s[90:91] op_sel_hi:[1,0]
	v_pk_mul_f32 v[178:179], v[100:101], s[90:91] op_sel_hi:[1,0]
	v_pk_mul_f32 v[180:181], v[102:103], s[90:91] op_sel_hi:[1,0]
	v_exp_f32_e32 v174, v174
	v_exp_f32_e32 v175, v175
	v_exp_f32_e32 v176, v176
	v_exp_f32_e32 v177, v177
	v_exp_f32_e32 v178, v178
	v_exp_f32_e32 v179, v179
	v_exp_f32_e32 v180, v180
	v_exp_f32_e32 v181, v181
	v_pk_add_f32 v[174:175], v[174:175], 1.0 op_sel_hi:[1,0]
	v_pk_add_f32 v[176:177], v[176:177], 1.0 op_sel_hi:[1,0]
	v_pk_add_f32 v[178:179], v[178:179], 1.0 op_sel_hi:[1,0]
	v_pk_add_f32 v[180:181], v[180:181], 1.0 op_sel_hi:[1,0]
	v_rcp_f32_e32 v174, v174
	v_rcp_f32_e32 v175, v175
	v_rcp_f32_e32 v176, v176
	v_rcp_f32_e32 v177, v177
	v_rcp_f32_e32 v178, v178
	v_rcp_f32_e32 v179, v179
	v_rcp_f32_e32 v180, v180
	v_rcp_f32_e32 v181, v181
	v_pk_mul_f32 v[108:109], v[108:109], v[174:175]
	v_pk_mul_f32 v[110:111], v[110:111], v[176:177]
	v_pk_mul_f32 v[100:101], v[100:101], v[178:179]
	v_pk_mul_f32 v[102:103], v[102:103], v[180:181]
	v_pk_mul_f32 v[108:109], v[104:105], v[108:109]
	v_pk_mul_f32 v[110:111], v[106:107], v[110:111]
	v_pk_mul_f32 v[100:101], v[96:97], v[100:101]
	v_pk_mul_f32 v[102:103], v[98:99], v[102:103]
	v_cvt_pk_bf16_f32 v108, v108, v109
	v_cvt_pk_bf16_f32 v109, v110, v111
	v_cvt_pk_bf16_f32 v100, v100, v101
	v_cvt_pk_bf16_f32 v101, v102, v103
	global_store_dwordx2 v155, v[108:109], s[34:35]
	global_store_dwordx2 v155, v[100:101], s[34:35] offset:128
	v_pk_mul_f32 v[92:93], v[92:93], v[208:209] op_sel_hi:[1,0]
	v_pk_mul_f32 v[94:95], v[94:95], v[208:209] op_sel_hi:[1,0]
	v_pk_mul_f32 v[84:85], v[84:85], v[208:209] op_sel_hi:[1,0]
	v_pk_mul_f32 v[86:87], v[86:87], v[208:209] op_sel_hi:[1,0]
	v_pk_mul_f32 v[88:89], v[88:89], v[208:209] op_sel_hi:[1,0]
	v_pk_mul_f32 v[90:91], v[90:91], v[208:209] op_sel_hi:[1,0]
	v_pk_mul_f32 v[80:81], v[80:81], v[208:209] op_sel_hi:[1,0]
	v_pk_mul_f32 v[82:83], v[82:83], v[208:209] op_sel_hi:[1,0]
	v_pk_mul_f32 v[174:175], v[92:93], s[90:91] op_sel_hi:[1,0]
	v_pk_mul_f32 v[176:177], v[94:95], s[90:91] op_sel_hi:[1,0]
	v_pk_mul_f32 v[178:179], v[84:85], s[90:91] op_sel_hi:[1,0]
	v_pk_mul_f32 v[180:181], v[86:87], s[90:91] op_sel_hi:[1,0]
	v_exp_f32_e32 v174, v174
	v_exp_f32_e32 v175, v175
	v_exp_f32_e32 v176, v176
	v_exp_f32_e32 v177, v177
	v_exp_f32_e32 v178, v178
	v_exp_f32_e32 v179, v179
	v_exp_f32_e32 v180, v180
	v_exp_f32_e32 v181, v181
	v_pk_add_f32 v[174:175], v[174:175], 1.0 op_sel_hi:[1,0]
	v_pk_add_f32 v[176:177], v[176:177], 1.0 op_sel_hi:[1,0]
	v_pk_add_f32 v[178:179], v[178:179], 1.0 op_sel_hi:[1,0]
	v_pk_add_f32 v[180:181], v[180:181], 1.0 op_sel_hi:[1,0]
	v_rcp_f32_e32 v174, v174
	v_rcp_f32_e32 v175, v175
	v_rcp_f32_e32 v176, v176
	v_rcp_f32_e32 v177, v177
	v_rcp_f32_e32 v178, v178
	v_rcp_f32_e32 v179, v179
	v_rcp_f32_e32 v180, v180
	v_rcp_f32_e32 v181, v181
	v_pk_mul_f32 v[92:93], v[92:93], v[174:175]
	v_pk_mul_f32 v[94:95], v[94:95], v[176:177]
	v_pk_mul_f32 v[84:85], v[84:85], v[178:179]
	v_pk_mul_f32 v[86:87], v[86:87], v[180:181]
	v_pk_mul_f32 v[92:93], v[88:89], v[92:93]
	v_pk_mul_f32 v[94:95], v[90:91], v[94:95]
	v_pk_mul_f32 v[84:85], v[80:81], v[84:85]
	v_pk_mul_f32 v[86:87], v[82:83], v[86:87]
	v_cvt_pk_bf16_f32 v92, v92, v93
	v_cvt_pk_bf16_f32 v93, v94, v95
	v_cvt_pk_bf16_f32 v84, v84, v85
	v_cvt_pk_bf16_f32 v85, v86, v87
	global_store_dwordx2 v156, v[92:93], s[34:35]
	global_store_dwordx2 v156, v[84:85], s[34:35] offset:128
	v_pk_mul_f32 v[76:77], v[76:77], v[208:209] op_sel:[0,1] op_sel_hi:[1,1]
	v_pk_mul_f32 v[78:79], v[78:79], v[208:209] op_sel:[0,1] op_sel_hi:[1,1]
	v_pk_mul_f32 v[68:69], v[68:69], v[208:209] op_sel:[0,1] op_sel_hi:[1,1]
	v_pk_mul_f32 v[70:71], v[70:71], v[208:209] op_sel:[0,1] op_sel_hi:[1,1]
	v_pk_mul_f32 v[72:73], v[72:73], v[208:209] op_sel:[0,1] op_sel_hi:[1,1]
	v_pk_mul_f32 v[74:75], v[74:75], v[208:209] op_sel:[0,1] op_sel_hi:[1,1]
	v_pk_mul_f32 v[64:65], v[64:65], v[208:209] op_sel:[0,1] op_sel_hi:[1,1]
	v_pk_mul_f32 v[66:67], v[66:67], v[208:209] op_sel:[0,1] op_sel_hi:[1,1]
	v_pk_mul_f32 v[174:175], v[76:77], s[90:91] op_sel_hi:[1,0]
	v_pk_mul_f32 v[176:177], v[78:79], s[90:91] op_sel_hi:[1,0]
	v_pk_mul_f32 v[178:179], v[68:69], s[90:91] op_sel_hi:[1,0]
	v_pk_mul_f32 v[180:181], v[70:71], s[90:91] op_sel_hi:[1,0]
	v_exp_f32_e32 v174, v174
	v_exp_f32_e32 v175, v175
	v_exp_f32_e32 v176, v176
	v_exp_f32_e32 v177, v177
	v_exp_f32_e32 v178, v178
	v_exp_f32_e32 v179, v179
	v_exp_f32_e32 v180, v180
	v_exp_f32_e32 v181, v181
	v_pk_add_f32 v[174:175], v[174:175], 1.0 op_sel_hi:[1,0]
	v_pk_add_f32 v[176:177], v[176:177], 1.0 op_sel_hi:[1,0]
	v_pk_add_f32 v[178:179], v[178:179], 1.0 op_sel_hi:[1,0]
	v_pk_add_f32 v[180:181], v[180:181], 1.0 op_sel_hi:[1,0]
	v_rcp_f32_e32 v174, v174
	v_rcp_f32_e32 v175, v175
	v_rcp_f32_e32 v176, v176
	v_rcp_f32_e32 v177, v177
	v_rcp_f32_e32 v178, v178
	v_rcp_f32_e32 v179, v179
	v_rcp_f32_e32 v180, v180
	v_rcp_f32_e32 v181, v181
	v_pk_mul_f32 v[76:77], v[76:77], v[174:175]
	v_pk_mul_f32 v[78:79], v[78:79], v[176:177]
	v_pk_mul_f32 v[68:69], v[68:69], v[178:179]
	v_pk_mul_f32 v[70:71], v[70:71], v[180:181]
	v_pk_mul_f32 v[76:77], v[72:73], v[76:77]
	v_pk_mul_f32 v[78:79], v[74:75], v[78:79]
	v_pk_mul_f32 v[68:69], v[64:65], v[68:69]
	v_pk_mul_f32 v[70:71], v[66:67], v[70:71]
	v_cvt_pk_bf16_f32 v76, v76, v77
	v_cvt_pk_bf16_f32 v77, v78, v79
	v_cvt_pk_bf16_f32 v68, v68, v69
	v_cvt_pk_bf16_f32 v69, v70, v71
	global_store_dwordx2 v157, v[76:77], s[34:35]
	global_store_dwordx2 v157, v[68:69], s[34:35] offset:128
	v_pk_mul_f32 v[60:61], v[60:61], v[210:211] op_sel_hi:[1,0]
	v_pk_mul_f32 v[62:63], v[62:63], v[210:211] op_sel_hi:[1,0]
	v_pk_mul_f32 v[52:53], v[52:53], v[210:211] op_sel_hi:[1,0]
	v_pk_mul_f32 v[54:55], v[54:55], v[210:211] op_sel_hi:[1,0]
	v_pk_mul_f32 v[56:57], v[56:57], v[210:211] op_sel_hi:[1,0]
	v_pk_mul_f32 v[58:59], v[58:59], v[210:211] op_sel_hi:[1,0]
	v_pk_mul_f32 v[48:49], v[48:49], v[210:211] op_sel_hi:[1,0]
	v_pk_mul_f32 v[50:51], v[50:51], v[210:211] op_sel_hi:[1,0]
	v_pk_mul_f32 v[174:175], v[60:61], s[90:91] op_sel_hi:[1,0]
	v_pk_mul_f32 v[176:177], v[62:63], s[90:91] op_sel_hi:[1,0]
	v_pk_mul_f32 v[178:179], v[52:53], s[90:91] op_sel_hi:[1,0]
	v_pk_mul_f32 v[180:181], v[54:55], s[90:91] op_sel_hi:[1,0]
	v_exp_f32_e32 v174, v174
	v_exp_f32_e32 v175, v175
	v_exp_f32_e32 v176, v176
	v_exp_f32_e32 v177, v177
	v_exp_f32_e32 v178, v178
	v_exp_f32_e32 v179, v179
	v_exp_f32_e32 v180, v180
	v_exp_f32_e32 v181, v181
	v_pk_add_f32 v[174:175], v[174:175], 1.0 op_sel_hi:[1,0]
	v_pk_add_f32 v[176:177], v[176:177], 1.0 op_sel_hi:[1,0]
	v_pk_add_f32 v[178:179], v[178:179], 1.0 op_sel_hi:[1,0]
	v_pk_add_f32 v[180:181], v[180:181], 1.0 op_sel_hi:[1,0]
	v_rcp_f32_e32 v174, v174
	v_rcp_f32_e32 v175, v175
	v_rcp_f32_e32 v176, v176
	v_rcp_f32_e32 v177, v177
	v_rcp_f32_e32 v178, v178
	v_rcp_f32_e32 v179, v179
	v_rcp_f32_e32 v180, v180
	v_rcp_f32_e32 v181, v181
	v_pk_mul_f32 v[60:61], v[60:61], v[174:175]
	v_pk_mul_f32 v[62:63], v[62:63], v[176:177]
	v_pk_mul_f32 v[52:53], v[52:53], v[178:179]
	v_pk_mul_f32 v[54:55], v[54:55], v[180:181]
	v_pk_mul_f32 v[60:61], v[56:57], v[60:61]
	v_pk_mul_f32 v[62:63], v[58:59], v[62:63]
	v_pk_mul_f32 v[52:53], v[48:49], v[52:53]
	v_pk_mul_f32 v[54:55], v[50:51], v[54:55]
	v_cvt_pk_bf16_f32 v60, v60, v61
	v_cvt_pk_bf16_f32 v61, v62, v63
	v_cvt_pk_bf16_f32 v52, v52, v53
	v_cvt_pk_bf16_f32 v53, v54, v55
	global_store_dwordx2 v158, v[60:61], s[34:35]
	global_store_dwordx2 v158, v[52:53], s[34:35] offset:128
	v_pk_mul_f32 v[44:45], v[44:45], v[210:211] op_sel:[0,1] op_sel_hi:[1,1]
	v_pk_mul_f32 v[46:47], v[46:47], v[210:211] op_sel:[0,1] op_sel_hi:[1,1]
	v_pk_mul_f32 v[36:37], v[36:37], v[210:211] op_sel:[0,1] op_sel_hi:[1,1]
	v_pk_mul_f32 v[38:39], v[38:39], v[210:211] op_sel:[0,1] op_sel_hi:[1,1]
	v_pk_mul_f32 v[40:41], v[40:41], v[210:211] op_sel:[0,1] op_sel_hi:[1,1]
	v_pk_mul_f32 v[42:43], v[42:43], v[210:211] op_sel:[0,1] op_sel_hi:[1,1]
	v_pk_mul_f32 v[32:33], v[32:33], v[210:211] op_sel:[0,1] op_sel_hi:[1,1]
	v_pk_mul_f32 v[34:35], v[34:35], v[210:211] op_sel:[0,1] op_sel_hi:[1,1]
	v_pk_mul_f32 v[174:175], v[44:45], s[90:91] op_sel_hi:[1,0]
	v_pk_mul_f32 v[176:177], v[46:47], s[90:91] op_sel_hi:[1,0]
	v_pk_mul_f32 v[178:179], v[36:37], s[90:91] op_sel_hi:[1,0]
	v_pk_mul_f32 v[180:181], v[38:39], s[90:91] op_sel_hi:[1,0]
	v_exp_f32_e32 v174, v174
	v_exp_f32_e32 v175, v175
	v_exp_f32_e32 v176, v176
	v_exp_f32_e32 v177, v177
	v_exp_f32_e32 v178, v178
	v_exp_f32_e32 v179, v179
	v_exp_f32_e32 v180, v180
	v_exp_f32_e32 v181, v181
	v_pk_add_f32 v[174:175], v[174:175], 1.0 op_sel_hi:[1,0]
	v_pk_add_f32 v[176:177], v[176:177], 1.0 op_sel_hi:[1,0]
	v_pk_add_f32 v[178:179], v[178:179], 1.0 op_sel_hi:[1,0]
	v_pk_add_f32 v[180:181], v[180:181], 1.0 op_sel_hi:[1,0]
	v_rcp_f32_e32 v174, v174
	v_rcp_f32_e32 v175, v175
	v_rcp_f32_e32 v176, v176
	v_rcp_f32_e32 v177, v177
	v_rcp_f32_e32 v178, v178
	v_rcp_f32_e32 v179, v179
	v_rcp_f32_e32 v180, v180
	v_rcp_f32_e32 v181, v181
	v_pk_mul_f32 v[44:45], v[44:45], v[174:175]
	v_pk_mul_f32 v[46:47], v[46:47], v[176:177]
	v_pk_mul_f32 v[36:37], v[36:37], v[178:179]
	v_pk_mul_f32 v[38:39], v[38:39], v[180:181]
	v_pk_mul_f32 v[44:45], v[40:41], v[44:45]
	v_pk_mul_f32 v[46:47], v[42:43], v[46:47]
	v_pk_mul_f32 v[36:37], v[32:33], v[36:37]
	v_pk_mul_f32 v[38:39], v[34:35], v[38:39]
	v_cvt_pk_bf16_f32 v44, v44, v45
	v_cvt_pk_bf16_f32 v45, v46, v47
	v_cvt_pk_bf16_f32 v36, v36, v37
	v_cvt_pk_bf16_f32 v37, v38, v39
	global_store_dwordx2 v159, v[44:45], s[34:35]
	global_store_dwordx2 v159, v[36:37], s[34:35] offset:128
	v_pk_mul_f32 v[28:29], v[28:29], v[212:213] op_sel_hi:[1,0]
	v_pk_mul_f32 v[30:31], v[30:31], v[212:213] op_sel_hi:[1,0]
	v_pk_mul_f32 v[20:21], v[20:21], v[212:213] op_sel_hi:[1,0]
	v_pk_mul_f32 v[22:23], v[22:23], v[212:213] op_sel_hi:[1,0]
	v_pk_mul_f32 v[24:25], v[24:25], v[212:213] op_sel_hi:[1,0]
	v_pk_mul_f32 v[26:27], v[26:27], v[212:213] op_sel_hi:[1,0]
	v_pk_mul_f32 v[16:17], v[16:17], v[212:213] op_sel_hi:[1,0]
	v_pk_mul_f32 v[18:19], v[18:19], v[212:213] op_sel_hi:[1,0]
	v_pk_mul_f32 v[174:175], v[28:29], s[90:91] op_sel_hi:[1,0]
	v_pk_mul_f32 v[176:177], v[30:31], s[90:91] op_sel_hi:[1,0]
	v_pk_mul_f32 v[178:179], v[20:21], s[90:91] op_sel_hi:[1,0]
	v_pk_mul_f32 v[180:181], v[22:23], s[90:91] op_sel_hi:[1,0]
	v_exp_f32_e32 v174, v174
	v_exp_f32_e32 v175, v175
	v_exp_f32_e32 v176, v176
	v_exp_f32_e32 v177, v177
	v_exp_f32_e32 v178, v178
	v_exp_f32_e32 v179, v179
	v_exp_f32_e32 v180, v180
	v_exp_f32_e32 v181, v181
	v_pk_add_f32 v[174:175], v[174:175], 1.0 op_sel_hi:[1,0]
	v_pk_add_f32 v[176:177], v[176:177], 1.0 op_sel_hi:[1,0]
	v_pk_add_f32 v[178:179], v[178:179], 1.0 op_sel_hi:[1,0]
	v_pk_add_f32 v[180:181], v[180:181], 1.0 op_sel_hi:[1,0]
	v_rcp_f32_e32 v174, v174
	v_rcp_f32_e32 v175, v175
	v_rcp_f32_e32 v176, v176
	v_rcp_f32_e32 v177, v177
	v_rcp_f32_e32 v178, v178
	v_rcp_f32_e32 v179, v179
	v_rcp_f32_e32 v180, v180
	v_rcp_f32_e32 v181, v181
	v_pk_mul_f32 v[28:29], v[28:29], v[174:175]
	v_pk_mul_f32 v[30:31], v[30:31], v[176:177]
	v_pk_mul_f32 v[20:21], v[20:21], v[178:179]
	v_pk_mul_f32 v[22:23], v[22:23], v[180:181]
	v_pk_mul_f32 v[28:29], v[24:25], v[28:29]
	v_pk_mul_f32 v[30:31], v[26:27], v[30:31]
	v_pk_mul_f32 v[20:21], v[16:17], v[20:21]
	v_pk_mul_f32 v[22:23], v[18:19], v[22:23]
	v_cvt_pk_bf16_f32 v28, v28, v29
	v_cvt_pk_bf16_f32 v29, v30, v31
	v_cvt_pk_bf16_f32 v20, v20, v21
	v_cvt_pk_bf16_f32 v21, v22, v23
	global_store_dwordx2 v160, v[28:29], s[34:35]
	global_store_dwordx2 v160, v[20:21], s[34:35] offset:128
	v_pk_mul_f32 v[12:13], v[12:13], v[212:213] op_sel:[0,1] op_sel_hi:[1,1]
	v_pk_mul_f32 v[14:15], v[14:15], v[212:213] op_sel:[0,1] op_sel_hi:[1,1]
	v_pk_mul_f32 v[4:5], v[4:5], v[212:213] op_sel:[0,1] op_sel_hi:[1,1]
	v_pk_mul_f32 v[6:7], v[6:7], v[212:213] op_sel:[0,1] op_sel_hi:[1,1]
	v_pk_mul_f32 v[8:9], v[8:9], v[212:213] op_sel:[0,1] op_sel_hi:[1,1]
	v_pk_mul_f32 v[10:11], v[10:11], v[212:213] op_sel:[0,1] op_sel_hi:[1,1]
	v_pk_mul_f32 v[0:1], v[0:1], v[212:213] op_sel:[0,1] op_sel_hi:[1,1]
	v_pk_mul_f32 v[2:3], v[2:3], v[212:213] op_sel:[0,1] op_sel_hi:[1,1]
	v_pk_mul_f32 v[174:175], v[12:13], s[90:91] op_sel_hi:[1,0]
	v_pk_mul_f32 v[176:177], v[14:15], s[90:91] op_sel_hi:[1,0]
	v_pk_mul_f32 v[178:179], v[4:5], s[90:91] op_sel_hi:[1,0]
	v_pk_mul_f32 v[180:181], v[6:7], s[90:91] op_sel_hi:[1,0]
	v_exp_f32_e32 v174, v174
	v_exp_f32_e32 v175, v175
	v_exp_f32_e32 v176, v176
	v_exp_f32_e32 v177, v177
	v_exp_f32_e32 v178, v178
	v_exp_f32_e32 v179, v179
	v_exp_f32_e32 v180, v180
	v_exp_f32_e32 v181, v181
	v_pk_add_f32 v[174:175], v[174:175], 1.0 op_sel_hi:[1,0]
	v_pk_add_f32 v[176:177], v[176:177], 1.0 op_sel_hi:[1,0]
	v_pk_add_f32 v[178:179], v[178:179], 1.0 op_sel_hi:[1,0]
	v_pk_add_f32 v[180:181], v[180:181], 1.0 op_sel_hi:[1,0]
	v_rcp_f32_e32 v174, v174
	v_rcp_f32_e32 v175, v175
	v_rcp_f32_e32 v176, v176
	v_rcp_f32_e32 v177, v177
	v_rcp_f32_e32 v178, v178
	v_rcp_f32_e32 v179, v179
	v_rcp_f32_e32 v180, v180
	v_rcp_f32_e32 v181, v181
	v_pk_mul_f32 v[12:13], v[12:13], v[174:175]
	v_pk_mul_f32 v[14:15], v[14:15], v[176:177]
	v_pk_mul_f32 v[4:5], v[4:5], v[178:179]
	v_pk_mul_f32 v[6:7], v[6:7], v[180:181]
	v_pk_mul_f32 v[12:13], v[8:9], v[12:13]
	v_pk_mul_f32 v[14:15], v[10:11], v[14:15]
	v_pk_mul_f32 v[4:5], v[0:1], v[4:5]
	v_pk_mul_f32 v[6:7], v[2:3], v[6:7]
	v_cvt_pk_bf16_f32 v12, v12, v13
	v_cvt_pk_bf16_f32 v13, v14, v15
	v_cvt_pk_bf16_f32 v4, v4, v5
	v_cvt_pk_bf16_f32 v5, v6, v7
	global_store_dwordx2 v161, v[12:13], s[34:35]
	global_store_dwordx2 v161, v[4:5], s[34:35] offset:128
	s_andn2_b64 vcc, exec, s[6:7]
	s_mov_b64 s[6:7], -1
	s_cbranch_vccnz .LBB0_543
	s_andn2_b64 vcc, exec, s[14:15]
	s_cbranch_vccnz .LBB0_542
	s_barrier
	s_branch .LBB0_542
